# P0b first_rows: the four modulation-scale loads per row issued with the row loads, all waits counted (were four serialized vmcnt(0) round trips per row)
# speedup vs baseline: 1.0080x; 1.0002x over previous
.LBB0_89:
	s_or_b64 exec, exec, s[8:9]
	v_lshl_add_u64 v[50:51], v[34:35], 0, v[30:31]
	global_load_dwordx4 v[34:37], v[50:51], off
	global_load_dwordx4 v[38:41], v[50:51], off offset:1024
	global_load_dwordx4 v[42:45], v[50:51], off offset:2048
	global_load_dwordx4 v[46:49], v[50:51], off offset:3072
	v_lshrrev_b32_e32 v0, 10, v0
	v_add_u32_e32 v0, 1, v0
	v_mov_b64_e32 v[50:51], s[10:11]
	v_cndmask_b32_e64 v0, v0, 0, s[6:7]
	v_mad_u64_u32 v[50:51], s[6:7], v0, s24, v[50:51]
	v_lshl_add_u64 v[54:55], v[50:51], 0, v[30:31]
	v_add_co_u32_e64 v86, s[6:7], s25, v54
	s_nop 1
	v_addc_co_u32_e64 v87, s[6:7], 0, v55, s[6:7]
	v_lshl_add_u64 v[88:89], v[54:55], 0, s[22:23]
	global_load_dwordx4 v[70:73], v[86:87], off
	global_load_dwordx4 v[74:77], v[88:89], off offset:1024
	global_load_dwordx4 v[78:81], v[88:89], off offset:2048
	global_load_dwordx4 v[82:85], v[88:89], off offset:3072
	v_lshl_add_u64 v[32:33], v[22:23], 0, v[32:33]
	s_waitcnt vmcnt(7)
	global_store_dwordx4 v[32:33], v[34:37], off
	s_waitcnt vmcnt(7)
	global_store_dwordx4 v[32:33], v[38:41], off offset:1024
	s_waitcnt vmcnt(7)
	global_store_dwordx4 v[32:33], v[42:45], off offset:2048
	s_waitcnt vmcnt(7)
	global_store_dwordx4 v[32:33], v[46:49], off offset:3072
	v_lshlrev_b64 v[32:33], 11, v[2:3]
	v_lshl_add_u64 v[56:57], v[24:25], 0, v[32:33]
	v_pk_mul_f32 v[54:55], v[6:7], v[36:37]
	v_pk_mul_f32 v[58:59], v[4:5], v[34:35]
	v_mul_f32_e32 v0, v35, v35
	v_mul_f32_e32 v35, v41, v41
	v_fmac_f32_e32 v35, v40, v40
	v_fmac_f32_e32 v0, v34, v34
	s_waitcnt vmcnt(7)
	v_pk_add_f32 v[52:53], v[72:73], 1.0 op_sel_hi:[1,0]
	v_pk_add_f32 v[50:51], v[70:71], 1.0 op_sel_hi:[1,0]
	v_pk_mul_f32 v[52:53], v[54:55], v[52:53]
	v_pk_mul_f32 v[50:51], v[58:59], v[50:51]
	v_pk_mul_f32 v[54:55], v[10:11], v[40:41]
	v_cvt_pk_bf16_f32 v50, v50, v51
	v_cvt_pk_bf16_f32 v51, v52, v53
	global_store_dwordx2 v[56:57], v[50:51], off
	v_pk_mul_f32 v[58:59], v[8:9], v[38:39]
	v_mul_f32_e32 v41, v47, v47
	v_fmac_f32_e32 v41, v46, v46
	s_waitcnt vmcnt(7)
	v_pk_add_f32 v[52:53], v[76:77], 1.0 op_sel_hi:[1,0]
	v_pk_add_f32 v[50:51], v[74:75], 1.0 op_sel_hi:[1,0]
	v_pk_mul_f32 v[52:53], v[54:55], v[52:53]
	v_pk_mul_f32 v[50:51], v[58:59], v[50:51]
	v_pk_mul_f32 v[54:55], v[14:15], v[44:45]
	v_cvt_pk_bf16_f32 v50, v50, v51
	v_cvt_pk_bf16_f32 v51, v52, v53
	global_store_dwordx2 v[56:57], v[50:51], off offset:512
	v_pk_mul_f32 v[58:59], v[12:13], v[42:43]
	s_waitcnt vmcnt(7)
	v_pk_add_f32 v[52:53], v[80:81], 1.0 op_sel_hi:[1,0]
	v_pk_add_f32 v[50:51], v[78:79], 1.0 op_sel_hi:[1,0]
	v_pk_mul_f32 v[52:53], v[54:55], v[52:53]
	v_pk_mul_f32 v[50:51], v[58:59], v[50:51]
	v_pk_mul_f32 v[54:55], v[18:19], v[48:49]
	v_cvt_pk_bf16_f32 v50, v50, v51
	v_cvt_pk_bf16_f32 v51, v52, v53
	global_store_dwordx2 v[56:57], v[50:51], off offset:1024
	v_mul_f32_e32 v32, v37, v37
	v_mul_f32_e32 v33, v39, v39
	v_mul_f32_e32 v37, v43, v43
	v_mul_f32_e32 v39, v45, v45
	v_fmac_f32_e32 v32, v36, v36
	v_fmac_f32_e32 v33, v38, v38
	v_mul_f32_e32 v43, v49, v49
	v_fmac_f32_e32 v37, v42, v42
	v_fmac_f32_e32 v39, v44, v44
	v_add_f32_e32 v33, v33, v35
	v_add_f32_e32 v0, v0, v32
	v_fmac_f32_e32 v43, v48, v48
	v_add_f32_e32 v34, v37, v39
	v_add_f32_e32 v0, v0, v33
	v_add_f32_e32 v35, v41, v43
	v_add_f32_e32 v0, v0, v34
	v_add_f32_e32 v0, v0, v35
	v_pk_mul_f32 v[58:59], v[16:17], v[46:47]
	s_waitcnt vmcnt(7)
	v_pk_add_f32 v[34:35], v[84:85], 1.0 op_sel_hi:[1,0]
	v_add_f32_dpp v0, v0, v0 quad_perm:[1,0,3,2] row_mask:0xf bank_mask:0xf bound_ctrl:1
	v_pk_add_f32 v[36:37], v[82:83], 1.0 op_sel_hi:[1,0]
	v_pk_mul_f32 v[34:35], v[54:55], v[34:35]
	v_add_f32_dpp v0, v0, v0 quad_perm:[2,3,0,1] row_mask:0xf bank_mask:0xf bound_ctrl:1
	v_pk_mul_f32 v[36:37], v[58:59], v[36:37]
	s_nop 0
	v_add_f32_dpp v0, v0, v0 row_half_mirror row_mask:0xf bank_mask:0xf bound_ctrl:1
	v_cvt_pk_bf16_f32 v36, v36, v37
	v_cvt_pk_bf16_f32 v37, v34, v35
	v_add_f32_dpp v0, v0, v0 row_mirror row_mask:0xf bank_mask:0xf bound_ctrl:1
	v_mov_b32_e32 v32, v0
	s_nop 1
	v_permlane16_swap_b32_e32 v0, v32
	v_add_f32_e32 v0, v0, v32
	v_mov_b32_e32 v32, v0
	s_nop 1
	v_permlane32_swap_b32_e32 v0, v32
	global_store_dwordx2 v[56:57], v[36:37], off offset:1536
	s_and_saveexec_b64 s[6:7], vcc
	s_cbranch_execz .LBB0_84
	v_add_f32_e32 v0, v0, v32
	v_lshlrev_b64 v[2:3], 6, v[2:3]
	v_cndmask_b32_e64 v0, 0, v0, s[4:5]
	v_lshl_add_u64 v[32:33], v[26:27], 0, v[2:3]
	v_mov_b32_e32 v2, v1
	v_mov_b32_e32 v3, v1
	global_store_dwordx4 v[32:33], v[0:3], off
	s_branch .LBB0_84
